# attention loops: in-loop vmcnt waits that only covered the Q loads (already complete after the loop-top wait) no longer stall on the K/V prefetch
# speedup vs baseline: 1.0052x; 1.0052x over previous
; __device__ __forceinline__ void ld16_sc1(u32x4& v, const void* p) { asm volatile("global_load_dwordx4 %0, %1, off sc1" : "=v"(v) : "v"(p) : "memory"); }
; __device__ __forceinline__ void ld16_sc1(f32x4& v, const float* p) { asm volatile("global_load_dwordx4 %0, %1, off sc1" : "=v"(v) : "v"(p) : "memory"); }
;   __device__ __forceinline__ const bf16_t* kptr(int t, int row) const { return zs + (size_t)(kidx(t, row) * d + r) * ZW + kcol; }
;   __device__ __forceinline__ const bf16_t* vptr(int t, int row) const { return zs + (size_t)(kidx(t, row) * d + r) * ZW + vcol; }
;   __device__ __forceinline__ const bf16_t* kptr(int t, int row) const { return zs + (size_t)(krow(t) * 64 + row) * ZW + 1024 + hc; }
; template <int DH, int KT, int NQT, bool PF, class Ctx>
; __device__ __forceinline__ void attn_item(unsigned char* smem, const Ctx& c) {
;     ...
;     __syncthreads();
;     if constexpr (PF) {
;       if (t + 1 < nt) {
; #pragma unroll
;         for (int i = 0; i < NCH; ++i) {
;           const int ci = tid + 256 * i, row = ci / CH, ch = ci % CH;
;           ld16_sc1(rk[i], c.kptr(t + 1, row) + ch * 8); ld16_sc1(rv[i], c.vptr(t + 1, row) + ch * 8);
;         }
;       }
;     }
;     if (c.active(t, wid)) {
;       constexpr int QG = NQT < 2 ? NQT : 2;
;       bf16x8 pfa[NQT][NKK];
; #pragma unroll
;       for (int g = 0; g < NQT; g += QG) {
;         f32x4 s[QG][NK4];
; #pragma unroll
;         for (int q = 0; q < QG; ++q)
; #pragma unroll
;           for (int k4 = 0; k4 < NK4; ++k4) s[q][k4] = (f32x4){0.f, 0.f, 0.f, 0.f};
; #pragma unroll
;         for (int k4 = 0; k4 < NK4; ++k4)
; #pragma unroll
;           for (int ks = 0; ks < NKS; ++ks) {
;             const bf16x8 kf = *(const bf16x8*)(sK + (16 * k4 + l15) * LDK + ks * 32 + quad * 8);
; #pragma unroll
;             for (int q = 0; q < QG; ++q) s[q][k4] = __builtin_amdgcn_mfma_f32_16x16x32_bf16(kf, qf[g + q][ks], s[q][k4], 0, 0, 0);
;           }
; #pragma unroll
;         for (int q = 0; q < QG; ++q) {
;           const int qt = g + q;
;           float mx = -1e30f;
; #pragma unroll
;           for (int k4 = 0; k4 < NK4; ++k4)
; #pragma unroll
;             for (int j = 0; j < 4; ++j) { const float v = c.score(t, wid, qt * 16 + l15, 16 * k4 + 4 * quad + j, s[q][k4][j]); s[q][k4][j] = v; mx = fmaxf(mx, v); }
.LBB0_180:
	s_waitcnt expcnt(7) lgkmcnt(15)
	s_barrier
	s_waitcnt vmcnt(0)
	ds_write_b128 v119, v[48:51]
	ds_write_b128 v119, v[52:55] offset:9216
	ds_write_b128 v120, v[56:59]
	ds_write_b128 v120, v[60:63] offset:9216
	v_add_u32_e32 v48, s89, v124
	v_max_i32_e32 v48, 0, v48
	v_min_i32_e32 v48, s96, v48
	v_add_u32_e32 v56, s89, v123
	v_lshlrev_b32_e32 v48, s93, v48
	v_max_i32_e32 v56, 0, v56
	v_add_u32_e32 v48, s92, v48
	v_min_i32_e32 v56, s96, v56
	v_mad_u64_u32 v[52:53], s[4:5], v48, s97, v[102:103]
	v_lshlrev_b32_e32 v56, s93, v56
	v_lshl_add_u64 v[48:49], v[52:53], 0, s[44:45]
	s_mov_b32 s61, s45
	v_add_u32_e32 v56, s92, v56
	v_lshl_add_u64 v[48:49], v[48:49], 0, v[104:105]
	v_lshl_add_u64 v[52:53], v[52:53], 0, s[60:61]
	v_mad_u64_u32 v[60:61], s[4:5], v56, s97, v[102:103]
	v_lshl_add_u64 v[48:49], v[48:49], 0, s[46:47]
	v_lshl_add_u64 v[52:53], v[52:53], 0, v[104:105]
	v_lshl_add_u64 v[56:57], v[60:61], 0, s[44:45]
	s_waitcnt lgkmcnt(0)
	s_barrier
	global_load_dwordx4 v[48:51], v[48:49], off sc1
	v_lshl_add_u64 v[52:53], v[52:53], 0, s[46:47]
	v_lshl_add_u64 v[56:57], v[56:57], 0, v[106:107]
	v_lshl_add_u64 v[60:61], v[60:61], 0, s[60:61]
	global_load_dwordx4 v[52:55], v[52:53], off sc1
	v_lshl_add_u64 v[56:57], v[56:57], 0, s[46:47]
	v_lshl_add_u64 v[60:61], v[60:61], 0, v[106:107]
	global_load_dwordx4 v[56:59], v[56:57], off sc1
	v_lshl_add_u64 v[60:61], v[60:61], 0, s[46:47]
	global_load_dwordx4 v[60:63], v[60:61], off sc1
	s_cmp_eq_u32 s33, s89
	s_cbranch_scc1 .LBB0_179
	v_cmp_lt_i32_e32 vcc, v215, v216
	v_add_u32_e32 v131, s89, v122
	ds_read_b128 v[72:75], v118 offset:64
	v_cndmask_b32_e32 v64, v214, v215, vcc
	v_lshlrev_b32_e32 v125, 2, v64
	ds_read_b128 v[64:67], v118
	v_subrev_u32_e32 v100, 64, v131
	v_cmp_lt_i32_e64 s[4:5], -1, v100
	v_cmp_gt_i32_e64 s[6:7], s50, v100
	v_cmp_lt_i32_e32 vcc, v217, v216
	s_waitcnt lgkmcnt(0)
	v_mfma_f32_16x16x32_bf16 v[68:71], v[64:67], v[44:47], 0
	ds_read_b128 v[76:79], v118 offset:2368
	v_cndmask_b32_e32 v112, v214, v217, vcc
	v_lshlrev_b32_e32 v126, 2, v112
	s_nop 0
	v_mfma_f32_16x16x32_bf16 v[64:67], v[64:67], v[32:35], 0
	ds_read_b128 v[80:83], v118 offset:4672
	ds_read_b128 v[108:111], v118 offset:6976
	v_mfma_f32_16x16x32_bf16 v[132:135], v[72:75], v[40:43], v[68:71]
	s_nop 0
	v_mfma_f32_16x16x32_bf16 v[72:75], v[72:75], v[36:39], v[64:67]
	s_nop 2
	ds_read_b128 v[64:67], v118 offset:2304
	s_waitcnt lgkmcnt(0)
	v_mfma_f32_16x16x32_bf16 v[68:71], v[64:67], v[44:47], 0
	v_mfma_f32_16x16x32_bf16 v[64:67], v[64:67], v[32:35], 0
	v_mfma_f32_16x16x32_bf16 v[88:91], v[76:79], v[40:43], v[68:71]
	v_mfma_f32_16x16x32_bf16 v[76:79], v[76:79], v[36:39], v[64:67]
	s_nop 5
	ds_read_b128 v[64:67], v118 offset:4608
	s_waitcnt lgkmcnt(0)
	v_mfma_f32_16x16x32_bf16 v[68:71], v[64:67], v[44:47], 0
	v_mfma_f32_16x16x32_bf16 v[64:67], v[64:67], v[32:35], 0
	v_mfma_f32_16x16x32_bf16 v[84:87], v[80:83], v[40:43], v[68:71]
	v_mfma_f32_16x16x32_bf16 v[68:71], v[80:83], v[36:39], v[64:67]
	s_nop 5
	ds_read_b128 v[64:67], v118 offset:6912
	s_waitcnt lgkmcnt(0)
	v_mfma_f32_16x16x32_bf16 v[80:83], v[64:67], v[44:47], 0
	v_mfma_f32_16x16x32_bf16 v[64:67], v[64:67], v[32:35], 0
	v_mfma_f32_16x16x32_bf16 v[80:83], v[108:111], v[40:43], v[80:83]
	v_mfma_f32_16x16x32_bf16 v[64:67], v[108:111], v[36:39], v[64:67]
	v_add_u32_e32 v110, s89, v121
	v_subrev_u32_e32 v108, 64, v110
	v_sub_u32_e32 v109, 64, v110
	v_max_i32_e32 v108, v108, v109
	v_cvt_f32_u32_e32 v100, v108
	v_cmp_gt_u32_e32 vcc, s94, v108
	s_and_b64 s[62:63], s[4:5], vcc
	s_and_b64 vcc, s[62:63], s[6:7]
	v_mul_f32_e32 v108, v101, v100
	v_fma_f32 v100, v132, s95, -v108
	v_subrev_u32_e32 v109, 63, v110
	v_sub_u32_e32 v111, 63, v110
	v_cndmask_b32_e32 v132, v190, v100, vcc
	v_subrev_u32_e32 v100, 63, v131
	v_max_i32_e32 v109, v109, v111
	v_cmp_gt_i32_e64 s[8:9], s50, v100
	v_cvt_f32_u32_e32 v100, v109
	v_subrev_u32_e32 v111, 62, v110
	v_sub_u32_e32 v112, 62, v110
	v_cmp_gt_u32_e32 vcc, s94, v109
	v_subrev_u32_e32 v109, 62, v131
	v_max_i32_e32 v111, v111, v112
	v_cmp_gt_i32_e64 s[10:11], s50, v109
	v_cvt_f32_u32_e32 v109, v111
	s_and_b64 s[64:65], s[4:5], vcc
	v_mul_f32_e32 v127, v101, v100
	s_and_b64 vcc, s[64:65], s[8:9]
	v_fma_f32 v100, v133, s95, -v127
	v_cndmask_b32_e32 v133, v190, v100, vcc
	v_cmp_gt_u32_e32 vcc, s94, v111
	s_and_b64 s[66:67], s[4:5], vcc
	v_mul_f32_e32 v128, v101, v109
	s_and_b64 vcc, s[66:67], s[10:11]
	v_fma_f32 v109, v134, s95, -v128
	v_subrev_u32_e32 v111, 61, v110
	v_sub_u32_e32 v112, 61, v110
	v_cndmask_b32_e32 v134, v190, v109, vcc
	v_subrev_u32_e32 v109, 61, v131
	v_max_i32_e32 v111, v111, v112
	v_cmp_gt_i32_e64 s[12:13], s50, v109
	v_cvt_f32_u32_e32 v109, v111
	v_cmp_gt_u32_e32 vcc, s94, v111
	s_and_b64 s[68:69], s[4:5], vcc
	s_and_b64 vcc, s[68:69], s[12:13]
	v_mul_f32_e32 v129, v101, v109
	v_fma_f32 v109, v135, s95, -v129
	v_subrev_u32_e32 v111, 48, v110
	v_sub_u32_e32 v112, 48, v110
	v_cndmask_b32_e32 v135, v190, v109, vcc
	v_subrev_u32_e32 v109, 48, v131
	v_max_i32_e32 v111, v111, v112
	v_cmp_gt_i32_e64 s[14:15], s50, v109
	v_cvt_f32_u32_e32 v109, v111
	v_cmp_gt_u32_e32 vcc, s94, v111
	v_subrev_u32_e32 v111, 47, v110
	v_sub_u32_e32 v112, 47, v110
	v_mul_f32_e32 v130, v101, v109
	v_subrev_u32_e32 v109, 47, v131
	v_max_i32_e32 v111, v111, v112
	v_cmp_gt_i32_e64 s[16:17], s50, v109
	v_cvt_f32_u32_e32 v109, v111
	s_and_b64 s[70:71], s[4:5], vcc
	s_and_b64 vcc, s[70:71], s[14:15]
	v_fma_f32 v88, v88, s95, -v130
	v_cndmask_b32_e32 v88, v190, v88, vcc
	v_cmp_gt_u32_e32 vcc, s94, v111
	s_and_b64 s[72:73], s[4:5], vcc
	v_mul_f32_e32 v111, v101, v109
; template <int DH, int KT, int NQT, bool PF, class Ctx>
; __device__ __forceinline__ void attn_item(unsigned char* smem, const Ctx& c) {
;     ...
;           for (int k4 = 0; k4 < NK4; ++k4)
; #pragma unroll
;             for (int j = 0; j < 4; ++j) { const float v = c.score(t, wid, qt * 16 + l15, 16 * k4 + 4 * quad + j, s[q][k4][j]); s[q][k4][j] = v; mx = fmaxf(mx, v); }
;           mx = fmaxf(mx, __shfl_xor(mx, 16)); mx = fmaxf(mx, __shfl_xor(mx, 32));
;           const float mnew = fmaxf(mrow[qt], mx);
;           if (__any(mnew > mrow[qt])) {
;             const float alpha = __builtin_amdgcn_exp2f(mrow[qt] - mnew);
;             mrow[qt] = mnew;
;             lrow[qt] *= alpha;
; #pragma unroll
;             for (int dt = 0; dt < NDT; ++dt) o[qt][dt] *= alpha;
;           }
	s_and_b64 vcc, s[72:73], s[16:17]
	v_fma_f32 v89, v89, s95, -v111
	v_subrev_u32_e32 v111, 46, v110
	v_sub_u32_e32 v112, 46, v110
	v_cndmask_b32_e32 v136, v190, v89, vcc
	v_subrev_u32_e32 v89, 46, v131
	v_max_i32_e32 v111, v111, v112
	v_cmp_gt_i32_e64 s[18:19], s50, v89
	v_cvt_f32_u32_e32 v89, v111
	v_cmp_gt_u32_e32 vcc, s94, v111
	v_subrev_u32_e32 v112, 45, v110
	v_sub_u32_e32 v113, 45, v110
	v_mul_f32_e32 v111, v101, v89
	v_fma_f32 v90, v90, s95, -v111
	v_subrev_u32_e32 v111, 45, v131
	v_max_i32_e32 v112, v112, v113
	v_cmp_gt_i32_e64 s[20:21], s50, v111
	v_cvt_f32_u32_e32 v111, v112
	s_and_b64 s[74:75], s[4:5], vcc
	s_and_b64 vcc, s[74:75], s[18:19]
	v_cndmask_b32_e32 v90, v190, v90, vcc
	v_cmp_gt_u32_e32 vcc, s94, v112
	v_max3_f32 v100, v132, s90, v133
	s_and_b64 s[76:77], s[4:5], vcc
	v_mul_f32_e32 v112, v101, v111
	v_max3_f32 v100, v100, v134, v135
	s_and_b64 vcc, s[76:77], s[20:21]
	v_fma_f32 v91, v91, s95, -v112
	v_max3_f32 v100, v100, v88, v136
	v_cndmask_b32_e32 v137, v190, v91, vcc
	v_max3_f32 v112, v100, v90, v137
	v_subrev_u32_e32 v100, 32, v110
	v_sub_u32_e32 v113, 32, v110
	v_subrev_u32_e32 v91, 32, v131
	v_max_i32_e32 v100, v100, v113
	v_cmp_gt_i32_e64 s[22:23], s50, v91
	v_cvt_f32_u32_e32 v91, v100
	v_cmp_gt_u32_e32 vcc, s94, v100
	v_sub_u32_e32 v113, 31, v110
	s_and_b64 s[78:79], s[4:5], vcc
	v_mul_f32_e32 v100, v101, v91
	v_fma_f32 v84, v84, s95, -v100
	v_subrev_u32_e32 v100, 31, v110
	v_max_i32_e32 v100, v100, v113
	v_cvt_f32_u32_e32 v193, v100
	s_and_b64 vcc, s[78:79], s[22:23]
	v_cndmask_b32_e32 v138, v190, v84, vcc
	v_subrev_u32_e32 v84, 31, v131
	v_cmp_gt_u32_e32 vcc, s94, v100
	v_mov_b32_e32 v100, v85
	v_cmp_gt_i32_e64 s[24:25], s50, v84
	v_pk_mul_f32 v[84:85], v[100:101], v[192:193]
	s_and_b64 s[80:81], s[4:5], vcc
	v_sub_f32_e32 v84, v84, v85
	v_subrev_u32_e32 v85, 30, v110
	v_sub_u32_e32 v100, 30, v110
	s_and_b64 vcc, s[80:81], s[24:25]
	v_max_i32_e32 v85, v85, v100
	v_cndmask_b32_e32 v139, v190, v84, vcc
	v_cmp_gt_u32_e32 vcc, s94, v85
	v_cvt_f32_u32_e32 v85, v85
	v_subrev_u32_e32 v84, 30, v131
	v_cmp_gt_i32_e64 s[26:27], s50, v84
	v_mov_b32_e32 v100, v86
	v_mov_b32_e32 v84, v192
	v_max3_f32 v142, v112, v138, v139
	v_pk_mul_f32 v[112:113], v[100:101], v[84:85]
	v_subrev_u32_e32 v100, 29, v110
	v_sub_f32_e32 v86, v112, v113
	v_sub_u32_e32 v112, 29, v110
	v_max_i32_e32 v100, v100, v112
	v_cvt_f32_u32_e32 v113, v100
	s_and_b64 s[82:83], s[4:5], vcc
	s_and_b64 vcc, s[82:83], s[26:27]
	v_cndmask_b32_e32 v140, v190, v86, vcc
	v_subrev_u32_e32 v86, 29, v131
	v_cmp_gt_u32_e32 vcc, s94, v100
	v_mov_b32_e32 v100, v87
	v_mov_b32_e32 v112, v192
	v_cmp_gt_i32_e64 s[28:29], s50, v86
	v_pk_mul_f32 v[86:87], v[100:101], v[112:113]
	s_and_b64 s[84:85], s[4:5], vcc
	v_sub_f32_e32 v86, v86, v87
	v_add_u32_e32 v87, -16, v110
	v_sub_u32_e32 v100, 16, v110
	s_and_b64 vcc, s[84:85], s[28:29]
	v_max_i32_e32 v87, v87, v100
	v_cndmask_b32_e32 v141, v190, v86, vcc
	v_cmp_gt_u32_e32 vcc, s94, v87
	v_cvt_f32_u32_e32 v87, v87
	v_add_u32_e32 v86, -16, v131
	v_cmp_gt_i32_e64 s[30:31], s50, v86
	v_mov_b32_e32 v100, v80
	v_mov_b32_e32 v86, v192
	v_pk_mul_f32 v[86:87], v[100:101], v[86:87]
	s_and_b64 s[34:35], s[4:5], vcc
	v_sub_f32_e32 v80, v86, v87
	v_add_u32_e32 v86, -15, v110
	v_sub_u32_e32 v87, 15, v110
	v_max_i32_e32 v86, v86, v87
	v_cvt_f32_u32_e32 v87, v86
	s_and_b64 vcc, s[34:35], s[30:31]
	v_max3_f32 v144, v142, v140, v141
	v_cndmask_b32_e32 v142, v190, v80, vcc
	v_add_u32_e32 v80, -15, v131
	v_cmp_gt_u32_e32 vcc, s94, v86
	v_mov_b32_e32 v100, v81
	v_mov_b32_e32 v86, v192
	v_cmp_gt_i32_e64 s[34:35], s50, v80
	v_pk_mul_f32 v[80:81], v[100:101], v[86:87]
	s_and_b64 s[36:37], s[4:5], vcc
	v_sub_f32_e32 v80, v80, v81
	v_add_u32_e32 v81, -14, v110
	v_sub_u32_e32 v87, 14, v110
	s_and_b64 vcc, s[36:37], s[34:35]
	v_max_i32_e32 v81, v81, v87
	v_cndmask_b32_e32 v143, v190, v80, vcc
	v_cmp_gt_u32_e32 vcc, s94, v81
	v_cvt_f32_u32_e32 v81, v81
	v_add_u32_e32 v80, -14, v131
	v_cmp_gt_i32_e64 s[36:37], s50, v80
	v_mov_b32_e32 v100, v82
	v_mov_b32_e32 v80, v192
	v_pk_mul_f32 v[80:81], v[100:101], v[80:81]
	s_and_b64 s[38:39], s[4:5], vcc
	v_sub_f32_e32 v80, v80, v81
	v_add_u32_e32 v81, -13, v110
	v_sub_u32_e32 v82, 13, v110
	s_and_b64 vcc, s[38:39], s[36:37]
	v_max_i32_e32 v81, v81, v82
	v_max3_f32 v86, v144, v142, v143
	v_cndmask_b32_e32 v144, v190, v80, vcc
	v_cmp_gt_u32_e32 vcc, s94, v81
	v_cvt_f32_u32_e32 v81, v81
	v_add_u32_e32 v80, -13, v131
	v_cmp_gt_i32_e64 s[38:39], s50, v80
	v_mov_b32_e32 v100, v83
	v_mov_b32_e32 v80, v192
	s_and_b64 vcc, s[4:5], vcc
	v_pk_mul_f32 v[80:81], v[100:101], v[80:81]
	s_and_b64 vcc, vcc, s[38:39]
	v_sub_f32_e32 v80, v80, v81
	v_cndmask_b32_e32 v100, v190, v80, vcc
	v_max3_f32 v80, v86, v144, v100
	ds_bpermute_b32 v81, v125, v80
	s_waitcnt lgkmcnt(0)
	v_max_f32_e32 v81, v81, v81
	v_max_f32_e32 v80, v80, v81
	ds_bpermute_b32 v81, v126, v80
	s_waitcnt lgkmcnt(0)
	v_max3_f32 v80, v98, v80, v81
	v_cmp_gt_f32_e32 vcc, v80, v98
	s_cbranch_vccz .LBB0_183
	v_sub_f32_e32 v81, v98, v80
	v_exp_f32_e32 v82, v81
	v_mov_b32_e32 v81, v99
	v_mov_b64_e32 v[98:99], v[80:81]
	v_mul_f32_e32 v96, v96, v82
	v_pk_mul_f32 v[30:31], v[30:31], v[82:83] op_sel_hi:[1,0]
	v_pk_mul_f32 v[28:29], v[28:29], v[82:83] op_sel_hi:[1,0]
	v_pk_mul_f32 v[14:15], v[14:15], v[82:83] op_sel_hi:[1,0]
	v_pk_mul_f32 v[12:13], v[12:13], v[82:83] op_sel_hi:[1,0]
	v_pk_mul_f32 v[18:19], v[18:19], v[82:83] op_sel_hi:[1,0]
	v_pk_mul_f32 v[16:17], v[16:17], v[82:83] op_sel_hi:[1,0]
	v_pk_mul_f32 v[22:23], v[22:23], v[82:83] op_sel_hi:[1,0]
	v_pk_mul_f32 v[20:21], v[20:21], v[82:83] op_sel_hi:[1,0]

; template <int DH, int KT, int NQT, bool PF, class Ctx>
; __device__ __forceinline__ void attn_item(unsigned char* smem, const Ctx& c) {
;     ...
;       for (int g = 0; g < NQT; g += QG) {
;         f32x4 s[QG][NK4];
; #pragma unroll
;         for (int q = 0; q < QG; ++q)
; #pragma unroll
;           for (int k4 = 0; k4 < NK4; ++k4) s[q][k4] = (f32x4){0.f, 0.f, 0.f, 0.f};
; #pragma unroll
;         for (int k4 = 0; k4 < NK4; ++k4)
; #pragma unroll
;           for (int ks = 0; ks < NKS; ++ks) {
;             const bf16x8 kf = *(const bf16x8*)(sK + (16 * k4 + l15) * LDK + ks * 32 + quad * 8);
; #pragma unroll
;             for (int q = 0; q < QG; ++q) s[q][k4] = __builtin_amdgcn_mfma_f32_16x16x32_bf16(kf, qf[g + q][ks], s[q][k4], 0, 0, 0);
;           }
; #pragma unroll
;         for (int q = 0; q < QG; ++q) {
;           const int qt = g + q;
;           float mx = -1e30f;
; #pragma unroll
;           for (int k4 = 0; k4 < NK4; ++k4)
; #pragma unroll
;             for (int j = 0; j < 4; ++j) { const float v = c.score(t, wid, qt * 16 + l15, 16 * k4 + 4 * quad + j, s[q][k4][j]); s[q][k4][j] = v; mx = fmaxf(mx, v); }
;           mx = fmaxf(mx, __shfl_xor(mx, 16)); mx = fmaxf(mx, __shfl_xor(mx, 32));
;           const float mnew = fmaxf(mrow[qt], mx);
;           if (__any(mnew > mrow[qt])) {
;             const float alpha = __builtin_amdgcn_exp2f(mrow[qt] - mnew);
;             mrow[qt] = mnew;
;             lrow[qt] *= alpha;
; #pragma unroll
;             for (int dt = 0; dt < NDT; ++dt) o[qt][dt] *= alpha;
;           }
.LBB0_215:
	ds_read_b128 v[136:139], v188
	ds_read_b128 v[156:159], v188 offset:64
	ds_read_b128 v[164:167], v188 offset:2304
	ds_read_b128 v[172:175], v188 offset:2368
	ds_read_b128 v[180:183], v188 offset:4608
	ds_read_b128 v[132:135], v188 offset:4672
	ds_read_b128 v[120:123], v188 offset:6912
	s_waitcnt lgkmcnt(6)
	v_mfma_f32_16x16x32_bf16 v[112:115], v[136:139], v[4:7], v[232:235]
	ds_read_b128 v[168:171], v188 offset:6976
	v_cmp_lt_i32_e32 vcc, v215, v216
	s_nop 0
	v_mfma_f32_16x16x32_bf16 v[116:119], v[136:139], v[16:19], v[236:239]
	s_waitcnt lgkmcnt(6)
	v_mfma_f32_16x16x32_bf16 v[128:131], v[156:159], v[8:11], v[112:115]
	s_nop 0
	v_mfma_f32_16x16x32_bf16 v[144:147], v[156:159], v[20:23], v[116:119]
	s_waitcnt lgkmcnt(5)
	v_mfma_f32_16x16x32_bf16 v[112:115], v[164:167], v[4:7], v[232:235]
	v_mfma_f32_16x16x32_bf16 v[116:119], v[164:167], v[16:19], v[236:239]
	s_waitcnt lgkmcnt(4)
	v_mfma_f32_16x16x32_bf16 v[124:127], v[172:175], v[8:11], v[112:115]
	v_mfma_f32_16x16x32_bf16 v[140:143], v[172:175], v[20:23], v[116:119]
	s_waitcnt lgkmcnt(3)
	v_mfma_f32_16x16x32_bf16 v[112:115], v[180:183], v[4:7], v[232:235]
	s_nop 2
	v_cndmask_b32_e32 v116, v214, v215, vcc
	v_lshlrev_b32_e32 v220, 2, v116
	v_max3_f32 v116, v128, s90, v129
	v_max3_f32 v148, v116, v130, v131
	s_waitcnt lgkmcnt(1)
	v_mfma_f32_16x16x32_bf16 v[116:119], v[120:123], v[4:7], v[232:235]
	v_max3_f32 v148, v148, v124, v125
	v_max3_f32 v148, v148, v126, v127
	v_cmp_lt_i32_e32 vcc, v217, v216
	v_mfma_f32_16x16x32_bf16 v[112:115], v[132:135], v[8:11], v[112:115]
	s_nop 0
	v_cndmask_b32_e32 v162, v214, v217, vcc
	v_lshlrev_b32_e32 v223, 2, v162
	s_waitcnt lgkmcnt(0)
	v_mfma_f32_16x16x32_bf16 v[116:119], v[168:171], v[8:11], v[116:119]
	s_nop 2
	v_max3_f32 v148, v148, v112, v113
	v_max3_f32 v148, v148, v114, v115
	s_nop 2
	v_max3_f32 v148, v148, v116, v117
	v_max3_f32 v160, v148, v118, v119
	ds_bpermute_b32 v161, v220, v160
	v_mfma_f32_16x16x32_bf16 v[148:151], v[180:183], v[16:19], v[236:239]
	v_mfma_f32_16x16x32_bf16 v[152:155], v[132:135], v[20:23], v[148:151]
	s_waitcnt lgkmcnt(0)
	s_nop 5
	v_max_f32_e32 v148, v161, v161
	v_max_f32_e32 v160, v160, v148
	v_mfma_f32_16x16x32_bf16 v[148:151], v[120:123], v[16:19], v[236:239]
	ds_bpermute_b32 v161, v223, v160
	s_waitcnt lgkmcnt(0)
	v_max3_f32 v230, v249, v160, v161
	v_mfma_f32_16x16x32_bf16 v[148:151], v[168:171], v[20:23], v[148:151]
	v_cmp_gt_f32_e32 vcc, v230, v249
	s_cbranch_vccz .LBB0_217
	v_max_f32_e32 v160, 0, v230
	v_sub_f32_e32 v232, v232, v230
	v_exp_f32_e64 v160, -v160
	v_sub_f32_e32 v233, v233, v230
	v_sub_f32_e32 v234, v234, v230
	v_sub_f32_e32 v235, v235, v230
	v_mul_f32_e32 v225, v225, v160
	v_pk_mul_f32 v[110:111], v[110:111], v[160:161] op_sel_hi:[1,0]
	v_pk_mul_f32 v[108:109], v[108:109], v[160:161] op_sel_hi:[1,0]
	v_pk_mul_f32 v[106:107], v[106:107], v[160:161] op_sel_hi:[1,0]
	v_pk_mul_f32 v[104:105], v[104:105], v[160:161] op_sel_hi:[1,0]
	v_pk_mul_f32 v[102:103], v[102:103], v[160:161] op_sel_hi:[1,0]
	v_pk_mul_f32 v[100:101], v[100:101], v[160:161] op_sel_hi:[1,0]
	v_pk_mul_f32 v[98:99], v[98:99], v[160:161] op_sel_hi:[1,0]
	v_pk_mul_f32 v[96:97], v[96:97], v[160:161] op_sel_hi:[1,0]
	v_sub_f32_e32 v128, v128, v230
	v_sub_f32_e32 v129, v129, v230
	v_sub_f32_e32 v130, v130, v230
	v_sub_f32_e32 v131, v131, v230
	v_sub_f32_e32 v124, v124, v230
	v_sub_f32_e32 v125, v125, v230
	v_sub_f32_e32 v126, v126, v230
	v_sub_f32_e32 v127, v127, v230
	v_sub_f32_e32 v112, v112, v230
	v_sub_f32_e32 v113, v113, v230
	v_sub_f32_e32 v114, v114, v230
	v_sub_f32_e32 v115, v115, v230
	v_sub_f32_e32 v116, v116, v230
	v_sub_f32_e32 v117, v117, v230
	v_sub_f32_e32 v118, v118, v230
	v_sub_f32_e32 v119, v119, v230

; template <int DH, int KT, int NQT, bool PF, class Ctx>
; __device__ __forceinline__ void attn_item(unsigned char* smem, const Ctx& c) {
;     ...
;       for (int g = 0; g < NQT; g += QG) {
;         f32x4 s[QG][NK4];
; #pragma unroll
;         for (int q = 0; q < QG; ++q)
; #pragma unroll
;           for (int k4 = 0; k4 < NK4; ++k4) s[q][k4] = (f32x4){0.f, 0.f, 0.f, 0.f};
; #pragma unroll
;         for (int k4 = 0; k4 < NK4; ++k4)
; #pragma unroll
;           for (int ks = 0; ks < NKS; ++ks) {
;             const bf16x8 kf = *(const bf16x8*)(sK + (16 * k4 + l15) * LDK + ks * 32 + quad * 8);
; #pragma unroll
;             for (int q = 0; q < QG; ++q) s[q][k4] = __builtin_amdgcn_mfma_f32_16x16x32_bf16(kf, qf[g + q][ks], s[q][k4], 0, 0, 0);
;           }
; #pragma unroll
;         for (int q = 0; q < QG; ++q) {
;           const int qt = g + q;
;           float mx = -1e30f;
; #pragma unroll
;           for (int k4 = 0; k4 < NK4; ++k4)
; #pragma unroll
;             for (int j = 0; j < 4; ++j) { const float v = c.score(t, wid, qt * 16 + l15, 16 * k4 + 4 * quad + j, s[q][k4][j]); s[q][k4][j] = v; mx = fmaxf(mx, v); }
;           mx = fmaxf(mx, __shfl_xor(mx, 16)); mx = fmaxf(mx, __shfl_xor(mx, 32));
;           const float mnew = fmaxf(mrow[qt], mx);
;           if (__any(mnew > mrow[qt])) {
;             const float alpha = __builtin_amdgcn_exp2f(mrow[qt] - mnew);
;             mrow[qt] = mnew;
;             lrow[qt] *= alpha;
; #pragma unroll
;             for (int dt = 0; dt < NDT; ++dt) o[qt][dt] *= alpha;
.LBB0_219:
	s_nop 0
	v_mfma_f32_16x16x32_bf16 v[160:163], v[136:139], v[28:31], v[240:243]
	s_nop 0
	v_mfma_f32_16x16x32_bf16 v[136:139], v[136:139], v[40:43], v[244:247]
	v_mfma_f32_16x16x32_bf16 v[184:187], v[156:159], v[36:39], v[160:163]
	s_nop 0
	v_mfma_f32_16x16x32_bf16 v[160:163], v[156:159], v[44:47], v[136:139]
	v_mfma_f32_16x16x32_bf16 v[136:139], v[164:167], v[28:31], v[240:243]
	v_mfma_f32_16x16x32_bf16 v[156:159], v[164:167], v[40:43], v[244:247]
	v_mfma_f32_16x16x32_bf16 v[176:179], v[172:175], v[36:39], v[136:139]
	v_mfma_f32_16x16x32_bf16 v[136:139], v[172:175], v[44:47], v[156:159]
	v_mfma_f32_16x16x32_bf16 v[156:159], v[180:183], v[28:31], v[240:243]
	v_mfma_f32_16x16x32_bf16 v[164:167], v[132:135], v[36:39], v[156:159]
	v_mfma_f32_16x16x32_bf16 v[172:175], v[180:183], v[40:43], v[244:247]
	s_nop 5
	v_max3_f32 v156, v184, s90, v185
	v_max3_f32 v180, v156, v186, v187
	v_max3_f32 v180, v180, v176, v177
	v_mfma_f32_16x16x32_bf16 v[156:159], v[120:123], v[28:31], v[240:243]
	v_max3_f32 v180, v180, v178, v179
	v_max3_f32 v180, v180, v164, v165
	v_max3_f32 v180, v180, v166, v167
	v_mfma_f32_16x16x32_bf16 v[156:159], v[168:171], v[36:39], v[156:159]
	v_mfma_f32_16x16x32_bf16 v[132:135], v[132:135], v[44:47], v[172:175]
	v_mfma_f32_16x16x32_bf16 v[120:123], v[120:123], v[40:43], v[244:247]
	s_nop 5
	v_max3_f32 v180, v180, v156, v157
	v_max3_f32 v180, v180, v158, v159
	ds_bpermute_b32 v172, v220, v180
	v_mfma_f32_16x16x32_bf16 v[120:123], v[168:171], v[44:47], v[120:123]
	s_waitcnt lgkmcnt(0)
	v_max_f32_e32 v172, v172, v172
	v_max_f32_e32 v172, v180, v172
	ds_bpermute_b32 v173, v223, v172
	s_waitcnt lgkmcnt(0)
	v_max3_f32 v172, v249, v172, v173
	v_cmp_gt_f32_e32 vcc, v172, v249
	s_cbranch_vccz .LBB0_221
	v_max_f32_e32 v168, 0, v172
	v_sub_f32_e32 v240, v240, v172
	v_exp_f32_e64 v168, -v168
	v_sub_f32_e32 v241, v241, v172
	v_sub_f32_e32 v242, v242, v172
	v_sub_f32_e32 v243, v243, v172
	v_mul_f32_e32 v193, v193, v168
	v_pk_mul_f32 v[78:79], v[78:79], v[168:169] op_sel_hi:[1,0]
	v_pk_mul_f32 v[76:77], v[76:77], v[168:169] op_sel_hi:[1,0]
	v_pk_mul_f32 v[66:67], v[66:67], v[168:169] op_sel_hi:[1,0]
	v_pk_mul_f32 v[64:65], v[64:65], v[168:169] op_sel_hi:[1,0]
	v_pk_mul_f32 v[54:55], v[54:55], v[168:169] op_sel_hi:[1,0]
	v_pk_mul_f32 v[52:53], v[52:53], v[168:169] op_sel_hi:[1,0]
	v_pk_mul_f32 v[50:51], v[50:51], v[168:169] op_sel_hi:[1,0]
	v_pk_mul_f32 v[48:49], v[48:49], v[168:169] op_sel_hi:[1,0]
	v_sub_f32_e32 v184, v184, v172
	v_sub_f32_e32 v185, v185, v172
	v_sub_f32_e32 v186, v186, v172
	v_sub_f32_e32 v187, v187, v172
	v_sub_f32_e32 v176, v176, v172
	v_sub_f32_e32 v177, v177, v172
	v_sub_f32_e32 v178, v178, v172
	v_sub_f32_e32 v179, v179, v172
	v_sub_f32_e32 v164, v164, v172
	v_sub_f32_e32 v165, v165, v172
	v_sub_f32_e32 v166, v166, v172
	v_sub_f32_e32 v167, v167, v172
	v_sub_f32_e32 v156, v156, v172
	v_sub_f32_e32 v157, v157, v172
	v_sub_f32_e32 v158, v158, v172
	v_sub_f32_e32 v159, v159, v172

; template <int DH, int KT, int NQT, bool PF, class Ctx>
; __device__ __forceinline__ void attn_item(unsigned char* smem, const Ctx& c) {
;     ...
;     __syncthreads();
;     if constexpr (PF) {
;       static_assert(!PF || NCH == 2 || NCH == 4, "wait lists below are written for two or four chunks per matrix");
;       if constexpr (NCH == 2) asm volatile("s_waitcnt vmcnt(0)" : "+v"(rk[0]), "+v"(rk[NCH - 1]), "+v"(rv[0]), "+v"(rv[NCH - 1]) :: "memory");
;       else asm volatile("s_waitcnt vmcnt(0)" : "+v"(rk[0]), "+v"(rk[1]), "+v"(rk[NCH - 2]), "+v"(rk[NCH - 1]), "+v"(rv[0]), "+v"(rv[1]), "+v"(rv[NCH - 2]), "+v"(rv[NCH - 1]) :: "memory");
; #pragma unroll
;       for (int i = 0; i < NCH; ++i) {
;         const int ci = tid + 256 * i, row = ci / CH, ch = ci % CH;
;         *(u32x4*)(sK + row * LDK + ch * 8) = rk[i]; *(u32x4*)(sV + row * LDK + ch * 8) = rv[i];
;       }
;     } else {
; #pragma unroll
;       for (int i = 0; i < NCH; ++i) {
;         const int ci = tid + 256 * i, row = ci / CH, ch = ci % CH;
;         *(u32x4*)(sK + row * LDK + ch * 8) = ld_agent_u32x4(c.kptr(t, row) + ch * 8);
;       }
; #pragma unroll
;       for (int i = 0; i < NCH; ++i) {
;         const int ci = tid + 256 * i, row = ci / CH, ch = ci % CH;
;         *(u32x4*)(sV + row * LDK + ch * 8) = ld_agent_u32x4(c.vptr(t, row) + ch * 8);
;       }
;     }
;     __syncthreads();
;     if constexpr (PF) {
;       if (t + 1 < nt) {
; #pragma unroll
;         for (int i = 0; i < NCH; ++i) {
;           const int ci = tid + 256 * i, row = ci / CH, ch = ci % CH;
;           ld16_sc1(rk[i], c.kptr(t + 1, row) + ch * 8); ld16_sc1(rv[i], c.vptr(t + 1, row) + ch * 8);
;         }
;       }
;     }
;     if (c.active(t, wid)) {
;       constexpr int QG = NQT < 2 ? NQT : 2;
;       bf16x8 pfa[NQT][NKK];
; #pragma unroll
;       for (int g = 0; g < NQT; g += QG) {
;         f32x4 s[QG][NK4];
; #pragma unroll
;         for (int q = 0; q < QG; ++q)
; #pragma unroll
;           for (int k4 = 0; k4 < NK4; ++k4) s[q][k4] = (f32x4){0.f, 0.f, 0.f, 0.f};
; #pragma unroll
;         for (int k4 = 0; k4 < NK4; ++k4)
; #pragma unroll
;           for (int ks = 0; ks < NKS; ++ks) {
;             const bf16x8 kf = *(const bf16x8*)(sK + (16 * k4 + l15) * LDK + ks * 32 + quad * 8);
; #pragma unroll
.LBB0_327:
	s_barrier
	s_waitcnt vmcnt(0)
	ds_write_b128 v157, v[96:99]
	ds_write_b128 v157, v[100:103] offset:16896
	ds_write_b128 v158, v[104:107]
	ds_write_b128 v158, v[108:111] offset:16896
	ds_write_b128 v159, v[112:115]
	ds_write_b128 v159, v[116:119] offset:16896
	ds_write_b128 v160, v[120:123]
	ds_write_b128 v160, v[124:127] offset:16896
	v_lshl_add_u64 v[96:97], v[146:147], 0, s[14:15]
	v_lshl_add_u64 v[100:101], v[132:133], 1, v[96:97]
	v_lshl_add_u64 v[96:97], v[100:101], 0, s[10:11]
	v_lshl_add_u64 v[104:105], v[144:145], 0, s[14:15]
	s_waitcnt lgkmcnt(0)
	s_barrier
	global_load_dwordx4 v[96:99], v[96:97], off sc1
	v_lshl_add_u64 v[100:101], v[100:101], 0, s[12:13]
	v_lshl_add_u64 v[108:109], v[134:135], 1, v[104:105]
	global_load_dwordx4 v[100:103], v[100:101], off sc1
	v_lshl_add_u64 v[104:105], v[108:109], 0, s[10:11]
	v_lshl_add_u64 v[112:113], v[142:143], 0, s[14:15]
	global_load_dwordx4 v[104:107], v[104:105], off sc1
	v_lshl_add_u64 v[108:109], v[108:109], 0, s[12:13]
	v_lshl_add_u64 v[116:117], v[136:137], 1, v[112:113]
	global_load_dwordx4 v[108:111], v[108:109], off sc1
	v_lshl_add_u64 v[112:113], v[116:117], 0, s[10:11]
	v_lshl_add_u64 v[120:121], v[140:141], 0, s[14:15]
	global_load_dwordx4 v[112:115], v[112:113], off sc1
	v_lshl_add_u64 v[116:117], v[116:117], 0, s[12:13]
	v_lshl_add_u64 v[124:125], v[138:139], 1, v[120:121]
	global_load_dwordx4 v[116:119], v[116:117], off sc1
	v_lshl_add_u64 v[120:121], v[124:125], 0, s[10:11]
	global_load_dwordx4 v[120:123], v[120:121], off sc1
	v_lshl_add_u64 v[124:125], v[124:125], 0, s[12:13]
	global_load_dwordx4 v[124:127], v[124:125], off sc1
	ds_read_b128 v[162:165], v156
	ds_read_b128 v[166:169], v156 offset:64
	s_waitcnt lgkmcnt(1)
	v_mfma_f32_16x16x32_bf16 v[162:165], v[162:165], v[72:75], 0
	ds_read_b128 v[170:173], v156 offset:128
	ds_read_b128 v[174:177], v156 offset:8576
	v_cmp_lt_i32_e32 vcc, v149, v150
	s_waitcnt lgkmcnt(2)
	v_mfma_f32_16x16x32_bf16 v[162:165], v[166:169], v[76:79], v[162:165]
	ds_read_b128 v[166:169], v156 offset:192
	v_cndmask_b32_e32 v154, v148, v149, vcc
	v_lshlrev_b32_e32 v154, 2, v154
	s_waitcnt lgkmcnt(2)
	v_mfma_f32_16x16x32_bf16 v[162:165], v[170:173], v[64:67], v[162:165]
	ds_read_b128 v[170:173], v156 offset:256
	v_cmp_lt_i32_e32 vcc, v151, v150
	s_waitcnt lgkmcnt(1)
	v_mfma_f32_16x16x32_bf16 v[162:165], v[166:169], v[68:71], v[162:165]
	ds_read_b128 v[166:169], v156 offset:320
	s_waitcnt lgkmcnt(1)
	v_mfma_f32_16x16x32_bf16 v[162:165], v[170:173], v[80:83], v[162:165]
	ds_read_b128 v[170:173], v156 offset:384
	s_waitcnt lgkmcnt(1)
	v_mfma_f32_16x16x32_bf16 v[162:165], v[166:169], v[84:87], v[162:165]
	ds_read_b128 v[166:169], v156 offset:448
	s_waitcnt lgkmcnt(1)
	v_mfma_f32_16x16x32_bf16 v[162:165], v[170:173], v[88:91], v[162:165]
	ds_read_b128 v[170:173], v156 offset:8448
	s_waitcnt lgkmcnt(1)
	v_mfma_f32_16x16x32_bf16 v[162:165], v[166:169], v[92:95], v[162:165]
	ds_read_b128 v[166:169], v156 offset:8512
	s_waitcnt lgkmcnt(1)
	v_mfma_f32_16x16x32_bf16 v[170:173], v[170:173], v[72:75], 0
	s_waitcnt lgkmcnt(0)
	v_mfma_f32_16x16x32_bf16 v[166:169], v[166:169], v[76:79], v[170:173]
	s_nop 5
	ds_read_b128 v[170:173], v156 offset:8640
	v_mfma_f32_16x16x32_bf16 v[166:169], v[174:177], v[64:67], v[166:169]
	ds_read_b128 v[174:177], v156 offset:8704
	s_waitcnt lgkmcnt(1)
	v_mfma_f32_16x16x32_bf16 v[166:169], v[170:173], v[68:71], v[166:169]
	ds_read_b128 v[170:173], v156 offset:8768
	s_waitcnt lgkmcnt(1)
	v_mfma_f32_16x16x32_bf16 v[166:169], v[174:177], v[80:83], v[166:169]
	ds_read_b128 v[174:177], v156 offset:8832
	s_waitcnt lgkmcnt(1)
	v_mfma_f32_16x16x32_bf16 v[166:169], v[170:173], v[84:87], v[166:169]
	ds_read_b128 v[170:173], v156 offset:8896
	s_waitcnt lgkmcnt(1)
	v_mfma_f32_16x16x32_bf16 v[166:169], v[174:177], v[88:91], v[166:169]
	s_waitcnt lgkmcnt(0)
	v_mfma_f32_16x16x32_bf16 v[170:173], v[170:173], v[92:95], v[166:169]
	s_nop 5
	v_mul_f32_e32 v169, 0x3db8aa3b, v162
	v_mul_f32_e32 v168, 0x3db8aa3b, v163
	v_max3_f32 v155, v169, s23, v168
	v_mul_f32_e32 v167, 0x3db8aa3b, v164
	v_mul_f32_e32 v166, 0x3db8aa3b, v165
	v_max3_f32 v155, v155, v167, v166
	v_mul_f32_e32 v165, 0x3db8aa3b, v170
	v_mul_f32_e32 v163, 0x3db8aa3b, v171
	v_max3_f32 v155, v155, v165, v163
	v_mul_f32_e32 v164, 0x3db8aa3b, v172
	v_mul_f32_e32 v162, 0x3db8aa3b, v173
	v_max3_f32 v170, v155, v164, v162
	ds_bpermute_b32 v171, v154, v170
	v_cndmask_b32_e32 v155, v148, v151, vcc
	v_lshlrev_b32_e32 v155, 2, v155
	s_waitcnt lgkmcnt(0)
	v_max_f32_e32 v171, v171, v171
	v_max_f32_e32 v170, v170, v171
	ds_bpermute_b32 v171, v155, v170
	s_waitcnt lgkmcnt(0)
	v_max3_f32 v170, v161, v170, v171
	v_cmp_gt_f32_e32 vcc, v170, v161
	s_cbranch_vccz .LBB0_326
	v_sub_f32_e32 v161, v161, v170
	v_exp_f32_e32 v172, v161
	v_mov_b32_e32 v161, v170
	v_pk_mul_f32 v[62:63], v[62:63], v[172:173] op_sel_hi:[1,0]
	v_pk_mul_f32 v[60:61], v[60:61], v[172:173] op_sel_hi:[1,0]
	v_pk_mul_f32 v[58:59], v[58:59], v[172:173] op_sel_hi:[1,0]
	v_pk_mul_f32 v[56:57], v[56:57], v[172:173] op_sel_hi:[1,0]
	v_pk_mul_f32 v[54:55], v[54:55], v[172:173] op_sel_hi:[1,0]
	v_pk_mul_f32 v[52:53], v[52:53], v[172:173] op_sel_hi:[1,0]
	v_pk_mul_f32 v[50:51], v[50:51], v[172:173] op_sel_hi:[1,0]
	v_pk_mul_f32 v[48:49], v[48:49], v[172:173] op_sel_hi:[1,0]
	v_pk_mul_f32 v[46:47], v[46:47], v[172:173] op_sel_hi:[1,0]
	v_pk_mul_f32 v[44:45], v[44:45], v[172:173] op_sel_hi:[1,0]
	v_pk_mul_f32 v[42:43], v[42:43], v[172:173] op_sel_hi:[1,0]
	v_pk_mul_f32 v[40:41], v[40:41], v[172:173] op_sel_hi:[1,0]
	v_pk_mul_f32 v[38:39], v[38:39], v[172:173] op_sel_hi:[1,0]
	v_pk_mul_f32 v[36:37], v[36:37], v[172:173] op_sel_hi:[1,0]
	v_pk_mul_f32 v[34:35], v[34:35], v[172:173] op_sel_hi:[1,0]
	v_pk_mul_f32 v[32:33], v[32:33], v[172:173] op_sel_hi:[1,0]
	v_pk_mul_f32 v[30:31], v[30:31], v[172:173] op_sel_hi:[1,0]
	v_pk_mul_f32 v[28:29], v[28:29], v[172:173] op_sel_hi:[1,0]
	v_pk_mul_f32 v[26:27], v[26:27], v[172:173] op_sel_hi:[1,0]
	v_pk_mul_f32 v[24:25], v[24:25], v[172:173] op_sel_hi:[1,0]
	v_pk_mul_f32 v[22:23], v[22:23], v[172:173] op_sel_hi:[1,0]
	v_pk_mul_f32 v[20:21], v[20:21], v[172:173] op_sel_hi:[1,0]
	v_pk_mul_f32 v[18:19], v[18:19], v[172:173] op_sel_hi:[1,0]
	v_pk_mul_f32 v[16:17], v[16:17], v[172:173] op_sel_hi:[1,0]
	v_pk_mul_f32 v[14:15], v[14:15], v[172:173] op_sel_hi:[1,0]
	v_pk_mul_f32 v[12:13], v[12:13], v[172:173] op_sel_hi:[1,0]
	v_pk_mul_f32 v[10:11], v[10:11], v[172:173] op_sel_hi:[1,0]
	v_pk_mul_f32 v[8:9], v[8:9], v[172:173] op_sel_hi:[1,0]
	v_pk_mul_f32 v[6:7], v[6:7], v[172:173] op_sel_hi:[1,0]
	v_pk_mul_f32 v[4:5], v[4:5], v[172:173] op_sel_hi:[1,0]
	v_pk_mul_f32 v[2:3], v[2:3], v[172:173] op_sel_hi:[1,0]
	v_pk_mul_f32 v[0:1], v[0:1], v[172:173] op_sel_hi:[1,0]
	v_mul_f32_e32 v128, v128, v172
	s_branch .LBB0_326

; template <int DH, int KT, int NQT, bool PF, class Ctx>
; __device__ __forceinline__ void attn_item(unsigned char* smem, const Ctx& c) {
;     ...
;     __syncthreads();
;     if constexpr (PF) {
;       static_assert(!PF || NCH == 2 || NCH == 4, "wait lists below are written for two or four chunks per matrix");
;       if constexpr (NCH == 2) asm volatile("s_waitcnt vmcnt(0)" : "+v"(rk[0]), "+v"(rk[NCH - 1]), "+v"(rv[0]), "+v"(rv[NCH - 1]) :: "memory");
;       else asm volatile("s_waitcnt vmcnt(0)" : "+v"(rk[0]), "+v"(rk[1]), "+v"(rk[NCH - 2]), "+v"(rk[NCH - 1]), "+v"(rv[0]), "+v"(rv[1]), "+v"(rv[NCH - 2]), "+v"(rv[NCH - 1]) :: "memory");
; #pragma unroll
;       for (int i = 0; i < NCH; ++i) {
;         const int ci = tid + 256 * i, row = ci / CH, ch = ci % CH;
;         *(u32x4*)(sK + row * LDK + ch * 8) = rk[i]; *(u32x4*)(sV + row * LDK + ch * 8) = rv[i];
;       }
;     } else {
; #pragma unroll
;       for (int i = 0; i < NCH; ++i) {
;         const int ci = tid + 256 * i, row = ci / CH, ch = ci % CH;
;         *(u32x4*)(sK + row * LDK + ch * 8) = ld_agent_u32x4(c.kptr(t, row) + ch * 8);
;       }
; #pragma unroll
;       for (int i = 0; i < NCH; ++i) {
;         const int ci = tid + 256 * i, row = ci / CH, ch = ci % CH;
;         *(u32x4*)(sV + row * LDK + ch * 8) = ld_agent_u32x4(c.vptr(t, row) + ch * 8);
;       }
;     }
;     __syncthreads();
;     if constexpr (PF) {
;       if (t + 1 < nt) {
; #pragma unroll
;         for (int i = 0; i < NCH; ++i) {
;           const int ci = tid + 256 * i, row = ci / CH, ch = ci % CH;
;           ld16_sc1(rk[i], c.kptr(t + 1, row) + ch * 8); ld16_sc1(rv[i], c.vptr(t + 1, row) + ch * 8);
;         }
;       }
;     }
;     if (c.active(t, wid)) {
;       constexpr int QG = NQT < 2 ? NQT : 2;
;       bf16x8 pfa[NQT][NKK];
; #pragma unroll
;       for (int g = 0; g < NQT; g += QG) {
;         f32x4 s[QG][NK4];
; #pragma unroll
;         for (int q = 0; q < QG; ++q)
; #pragma unroll
;           for (int k4 = 0; k4 < NK4; ++k4) s[q][k4] = (f32x4){0.f, 0.f, 0.f, 0.f};
; #pragma unroll
;         for (int k4 = 0; k4 < NK4; ++k4)
; #pragma unroll
;           for (int ks = 0; ks < NKS; ++ks) {
;             const bf16x8 kf = *(const bf16x8*)(sK + (16 * k4 + l15) * LDK + ks * 32 + quad * 8);
; #pragma unroll
.LBB0_508:
	s_barrier
	s_waitcnt vmcnt(0)
	s_mov_b32 s2, s33
	s_add_i32 s33, s33, 1
	s_min_i32 s3, s33, s0
	s_lshl_b32 s3, s3, 6
	ds_write_b128 v195, v[96:99]
	ds_write_b128 v195, v[100:103] offset:9216
	ds_write_b128 v196, v[104:107]
	ds_write_b128 v196, v[108:111] offset:9216
	v_add_u32_e32 v96, s3, v193
	v_mov_b64_e32 v[104:105], s[10:11]
	v_mad_i64_i32 v[96:97], vcc, v96, s12, v[104:105]
	v_lshl_add_u64 v[96:97], v[96:97], 0, s[14:15]
	v_add_u32_e32 v106, s3, v194
	v_lshl_add_u64 v[100:101], v[154:155], 1, v[96:97]
	v_mad_i64_i32 v[104:105], vcc, v106, s12, v[104:105]
	v_lshl_add_u64 v[96:97], v[100:101], 0, s[16:17]
	v_lshl_add_u64 v[104:105], v[104:105], 0, s[14:15]
	s_waitcnt lgkmcnt(0)
	s_barrier
	global_load_dwordx4 v[96:99], v[96:97], off sc1
	v_lshl_add_u64 v[100:101], v[100:101], 0, s[4:5]
	v_lshl_add_u64 v[108:109], v[156:157], 1, v[104:105]
	global_load_dwordx4 v[100:103], v[100:101], off sc1
	v_lshl_add_u64 v[104:105], v[108:109], 0, s[16:17]
	s_cmp_ge_u32 s2, s1
	global_load_dwordx4 v[104:107], v[104:105], off sc1
	v_lshl_add_u64 v[108:109], v[108:109], 0, s[4:5]
	s_cselect_b64 vcc, -1, 0
	s_cmp_lt_u32 s2, s9
	s_cselect_b64 s[2:3], -1, 0
	global_load_dwordx4 v[108:111], v[108:109], off sc1
	s_and_b64 s[2:3], vcc, s[2:3]
	s_andn2_b64 vcc, exec, s[2:3]
	s_cbranch_vccnz .LBB0_507
	v_add_u32_e32 v228, v142, v192
	ds_read_b128 v[112:115], v228
	ds_read_b128 v[116:119], v228 offset:64
	v_and_b32_e32 v128, 64, v163
	v_xor_b32_e32 v132, 16, v163
	v_add_u32_e32 v214, 64, v128
	s_waitcnt lgkmcnt(1)
	v_mfma_f32_16x16x32_bf16 v[120:123], v[112:115], v[92:95], 0
	v_cmp_lt_i32_e32 vcc, v132, v214
	v_add_u32_e32 v215, s8, v197
	v_add_u32_e32 v208, 0xe8, v215
	s_nop 0
	v_mfma_f32_16x16x32_bf16 v[124:127], v[112:115], v[80:83], 0
	ds_read_b128 v[112:115], v228 offset:2304
	v_add_u32_e32 v209, 0xe9, v215
	v_add_u32_e32 v212, 0xea, v215
	s_waitcnt lgkmcnt(1)
	v_mfma_f32_16x16x32_bf16 v[128:131], v[116:119], v[88:91], v[120:123]
	v_add_u32_e32 v213, 0xeb, v215
	v_add_u32_e32 v225, 0xf8, v215
	v_add_u32_e32 v224, 0xf9, v215
	v_cndmask_b32_e32 v120, v163, v132, vcc
	v_lshlrev_b32_e32 v207, 2, v120
	s_nop 0
	v_mfma_f32_16x16x32_bf16 v[136:139], v[116:119], v[84:87], v[124:127]
	ds_read_b128 v[116:119], v228 offset:2368
	ds_read_b128 v[120:123], v228 offset:4608
	v_add_u32_e32 v222, 0xfa, v215
	v_add_u32_e32 v220, 0xfb, v215
	s_waitcnt lgkmcnt(2)
	v_mfma_f32_16x16x32_bf16 v[124:127], v[112:115], v[92:95], 0
	v_cndmask_b32_e64 v132, v208, 0, s[6:7]
	v_cndmask_b32_e64 v200, v209, 0, s[96:97]
	v_cndmask_b32_e64 v201, v212, 0, s[94:95]
	v_cndmask_b32_e64 v202, v213, 0, s[92:93]
	v_cndmask_b32_e64 v203, 0, v225, s[90:91]
	v_cndmask_b32_e64 v204, 0, v224, s[88:89]
	v_cndmask_b32_e64 v205, 0, v222, s[86:87]
	v_cndmask_b32_e64 v206, 0, v220, s[84:85]
	v_lshlrev_b32_e32 v199, 2, v132
	v_lshlrev_b32_e32 v200, 2, v200
	s_waitcnt lgkmcnt(1)
	v_mfma_f32_16x16x32_bf16 v[124:127], v[116:119], v[88:91], v[124:127]
	v_lshlrev_b32_e32 v201, 2, v201
	v_lshlrev_b32_e32 v202, 2, v202
	v_lshlrev_b32_e32 v203, 2, v203
	v_lshlrev_b32_e32 v204, 2, v204
	v_lshlrev_b32_e32 v205, 2, v205
	v_lshlrev_b32_e32 v206, 2, v206
	ds_read_b32 v199, v199 offset:18432
	ds_read_b32 v200, v200 offset:18432
	ds_read_b32 v201, v201 offset:18432
	ds_read_b32 v202, v202 offset:18432
	ds_read_b32 v203, v203 offset:18432
	ds_read_b32 v204, v204 offset:18432
	ds_read_b32 v205, v205 offset:18432
	ds_read_b32 v206, v206 offset:18432
	s_waitcnt lgkmcnt(7)
	v_fmac_f32_e32 v199, 0x3e000000, v128
	s_waitcnt lgkmcnt(6)
	v_fmac_f32_e32 v200, 0x3e000000, v129
	v_mul_f32_e32 v128, 0x3fb8aa3b, v199
	v_mul_f32_e32 v129, 0x3fb8aa3b, v200
	s_waitcnt lgkmcnt(5)
	v_fmac_f32_e32 v201, 0x3e000000, v130
	v_cndmask_b32_e64 v199, v128, v164, s[6:7]
	v_cndmask_b32_e64 v200, v129, v164, s[96:97]
	v_mul_f32_e32 v129, 0x3fb8aa3b, v201
	s_waitcnt lgkmcnt(4)
	v_fmac_f32_e32 v202, 0x3e000000, v131
	s_waitcnt lgkmcnt(3)
	v_fmac_f32_e32 v203, 0x3e000000, v124
	s_waitcnt lgkmcnt(2)
	v_fmac_f32_e32 v204, 0x3e000000, v125
	v_max_f32_e32 v128, 0xf149f2ca, v199
	v_cndmask_b32_e64 v201, v129, v164, s[94:95]
	v_mul_f32_e32 v129, 0x3fb8aa3b, v202
	v_mul_f32_e32 v124, 0x3fb8aa3b, v203
	v_mul_f32_e32 v125, 0x3fb8aa3b, v204
	s_waitcnt lgkmcnt(1)
	v_fmac_f32_e32 v205, 0x3e000000, v126
	v_max3_f32 v128, v128, v200, v201
	v_cndmask_b32_e64 v202, v129, v164, s[92:93]
	v_cndmask_b32_e64 v203, v164, v124, s[90:91]
	v_cndmask_b32_e64 v204, v164, v125, s[88:89]
	v_mul_f32_e32 v125, 0x3fb8aa3b, v205
	s_waitcnt lgkmcnt(0)
	v_fmac_f32_e32 v206, 0x3e000000, v127
	v_max3_f32 v124, v128, v202, v203
	v_cndmask_b32_e64 v205, v164, v125, s[86:87]
	v_mul_f32_e32 v125, 0x3fb8aa3b, v206
	v_max3_f32 v124, v124, v204, v205
	v_cndmask_b32_e64 v206, v164, v125, s[84:85]
	v_max3_f32 v216, v124, v206, s13
	ds_bpermute_b32 v217, v207, v216
	ds_read_b128 v[124:127], v228 offset:4672
	v_xor_b32_e32 v198, 32, v163
	v_cmp_lt_i32_e32 vcc, v198, v214
	v_mfma_f32_16x16x32_bf16 v[132:135], v[112:115], v[80:83], 0
	s_nop 0
	v_cndmask_b32_e32 v128, v163, v198, vcc
	s_waitcnt lgkmcnt(1)
	v_max_f32_e32 v198, v217, v217
	v_lshlrev_b32_e32 v214, 2, v128
	v_mfma_f32_16x16x32_bf16 v[128:131], v[120:123], v[80:83], 0
	v_max_f32_e32 v198, v216, v198
	ds_bpermute_b32 v216, v214, v198
	s_waitcnt lgkmcnt(0)
	v_max3_f32 v198, v191, v198, v216
	v_mfma_f32_16x16x32_bf16 v[132:135], v[116:119], v[84:87], v[132:135]
	v_cmp_gt_f32_e32 vcc, v198, v191
	v_mfma_f32_16x16x32_bf16 v[128:131], v[124:127], v[84:87], v[128:131]
	s_cbranch_vccz .LBB0_511
	v_sub_f32_e32 v191, v191, v198
	v_exp_f32_e32 v216, v191
	v_mov_b32_e32 v191, v198
	v_mul_f32_e32 v168, v168, v216
	v_pk_mul_f32 v[62:63], v[62:63], v[216:217] op_sel_hi:[1,0]
	v_pk_mul_f32 v[60:61], v[60:61], v[216:217] op_sel_hi:[1,0]
	v_pk_mul_f32 v[58:59], v[58:59], v[216:217] op_sel_hi:[1,0]
	v_pk_mul_f32 v[56:57], v[56:57], v[216:217] op_sel_hi:[1,0]
	v_pk_mul_f32 v[54:55], v[54:55], v[216:217] op_sel_hi:[1,0]
	v_pk_mul_f32 v[52:53], v[52:53], v[216:217] op_sel_hi:[1,0]
	v_pk_mul_f32 v[50:51], v[50:51], v[216:217] op_sel_hi:[1,0]
	v_pk_mul_f32 v[48:49], v[48:49], v[216:217] op_sel_hi:[1,0]

; template <int DH, int KT, int NQT, bool PF, class Ctx>
; __device__ __forceinline__ void attn_item(unsigned char* smem, const Ctx& c) {
;     ...
;       for (int g = 0; g < NQT; g += QG) {
;         f32x4 s[QG][NK4];
; #pragma unroll
;         for (int q = 0; q < QG; ++q)
; #pragma unroll
;           for (int k4 = 0; k4 < NK4; ++k4) s[q][k4] = (f32x4){0.f, 0.f, 0.f, 0.f};
; #pragma unroll
;         for (int k4 = 0; k4 < NK4; ++k4)
; #pragma unroll
;           for (int ks = 0; ks < NKS; ++ks) {
;             const bf16x8 kf = *(const bf16x8*)(sK + (16 * k4 + l15) * LDK + ks * 32 + quad * 8);
; #pragma unroll
;             for (int q = 0; q < QG; ++q) s[q][k4] = __builtin_amdgcn_mfma_f32_16x16x32_bf16(kf, qf[g + q][ks], s[q][k4], 0, 0, 0);
;           }
; #pragma unroll
;         for (int q = 0; q < QG; ++q) {
;           const int qt = g + q;
;           float mx = -1e30f;
; #pragma unroll
;           for (int k4 = 0; k4 < NK4; ++k4)
; #pragma unroll
;             for (int j = 0; j < 4; ++j) { const float v = c.score(t, wid, qt * 16 + l15, 16 * k4 + 4 * quad + j, s[q][k4][j]); s[q][k4][j] = v; mx = fmaxf(mx, v); }
;           mx = fmaxf(mx, __shfl_xor(mx, 16)); mx = fmaxf(mx, __shfl_xor(mx, 32));
;           const float mnew = fmaxf(mrow[qt], mx);
;           if (__any(mnew > mrow[qt])) {
;             const float alpha = __builtin_amdgcn_exp2f(mrow[qt] - mnew);
;             mrow[qt] = mnew;
;             lrow[qt] *= alpha;
; #pragma unroll
;             for (int dt = 0; dt < NDT; ++dt) o[qt][dt] *= alpha;
;           }
.LBB0_513:
	s_nop 0
	v_mfma_f32_16x16x32_bf16 v[112:115], v[112:115], v[76:79], 0
	v_cndmask_b32_e64 v225, 0, v225, s[42:43]
	v_cndmask_b32_e64 v229, 0, v208, s[56:57]
	v_lshlrev_b32_e32 v225, 2, v225
	s_nop 0
	v_mfma_f32_16x16x32_bf16 v[230:233], v[116:119], v[72:75], v[112:115]
	v_lshlrev_b32_e32 v229, 2, v229
	ds_read_b32 v225, v225 offset:18432
	ds_read_b32 v229, v229 offset:18432
	v_mfma_f32_16x16x32_bf16 v[112:115], v[120:123], v[76:79], 0
	s_nop 0
	v_mfma_f32_16x16x32_bf16 v[116:119], v[120:123], v[64:67], 0
	v_mfma_f32_16x16x32_bf16 v[128:131], v[124:127], v[72:75], v[112:115]
	s_nop 0
	v_mfma_f32_16x16x32_bf16 v[112:115], v[124:127], v[68:71], v[116:119]
	ds_read_b128 v[124:127], v228 offset:6976
	s_waitcnt lgkmcnt(1)
	s_nop 3
	v_fmac_f32_e32 v229, 0x3e000000, v128
	v_mul_f32_e32 v128, 0x3fb8aa3b, v229
	ds_read_b128 v[116:119], v228 offset:6912
	s_waitcnt lgkmcnt(0)
	v_mfma_f32_16x16x32_bf16 v[120:123], v[116:119], v[76:79], 0
	v_cndmask_b32_e64 v229, 0, v209, s[58:59]
	v_lshlrev_b32_e32 v229, 2, v229
	ds_read_b32 v229, v229 offset:18432
	v_mfma_f32_16x16x32_bf16 v[116:119], v[116:119], v[64:67], 0
	v_cndmask_b32_e64 v128, v164, v128, s[56:57]
	s_waitcnt lgkmcnt(0)
	v_fmac_f32_e32 v229, 0x3e000000, v129
	v_mfma_f32_16x16x32_bf16 v[120:123], v[124:127], v[72:75], v[120:123]
	v_mul_f32_e32 v129, 0x3fb8aa3b, v229
	v_cndmask_b32_e64 v129, v164, v129, s[58:59]
	v_mfma_f32_16x16x32_bf16 v[116:119], v[124:127], v[68:71], v[116:119]
	v_cndmask_b32_e64 v125, v223, 0, s[50:51]
	v_lshlrev_b32_e32 v125, 2, v125
	v_cndmask_b32_e64 v126, v226, 0, s[44:45]
	ds_read_b32 v125, v125 offset:18432
	v_lshlrev_b32_e32 v126, 2, v126
	ds_read_b32 v126, v126 offset:18432
	v_fmac_f32_e32 v225, 0x3e000000, v120
	v_mul_f32_e32 v120, 0x3fb8aa3b, v225
	v_cndmask_b32_e64 v124, v221, 0, s[48:49]
	v_cndmask_b32_e64 v127, v227, 0, s[46:47]
	v_cndmask_b32_e64 v225, v164, v120, s[42:43]
	v_cndmask_b32_e64 v120, 0, v224, s[40:41]
	v_lshlrev_b32_e32 v124, 2, v124
	v_lshlrev_b32_e32 v127, 2, v127
	v_lshlrev_b32_e32 v120, 2, v120
	ds_read_b32 v124, v124 offset:18432
	ds_read_b32 v127, v127 offset:18432
	ds_read_b32 v120, v120 offset:18432
	s_waitcnt lgkmcnt(2)
	v_fmac_f32_e32 v124, 0x3e000000, v230
	v_mul_f32_e32 v124, 0x3fb8aa3b, v124
	s_waitcnt lgkmcnt(0)
	v_fmac_f32_e32 v120, 0x3e000000, v121
	v_cndmask_b32_e64 v121, 0, v222, s[38:39]
	v_lshlrev_b32_e32 v121, 2, v121
	ds_read_b32 v121, v121 offset:18432
	v_fmac_f32_e32 v125, 0x3e000000, v231
	v_mul_f32_e32 v125, 0x3fb8aa3b, v125
	v_fmac_f32_e32 v127, 0x3e000000, v233
	v_cndmask_b32_e64 v124, v124, v164, s[48:49]
	s_waitcnt lgkmcnt(0)
	v_fmac_f32_e32 v121, 0x3e000000, v122
	v_mul_f32_e32 v121, 0x3fb8aa3b, v121
	v_cndmask_b32_e64 v222, v164, v121, s[38:39]
	v_cndmask_b32_e64 v121, 0, v220, s[36:37]
	v_lshlrev_b32_e32 v121, 2, v121
	ds_read_b32 v121, v121 offset:18432
	v_fmac_f32_e32 v126, 0x3e000000, v232
	v_cndmask_b32_e64 v125, v125, v164, s[50:51]
	v_mul_f32_e32 v126, 0x3fb8aa3b, v126
	v_mul_f32_e32 v127, 0x3fb8aa3b, v127
	v_max3_f32 v228, v124, s13, v125
	v_cndmask_b32_e64 v126, v126, v164, s[44:45]
	v_cndmask_b32_e64 v127, v127, v164, s[46:47]
	v_max3_f32 v228, v228, v126, v127
	v_max3_f32 v229, v228, v128, v129
	v_cndmask_b32_e64 v228, 0, v212, s[54:55]
	v_lshlrev_b32_e32 v228, 2, v228
	ds_read_b32 v228, v228 offset:18432
	v_mul_f32_e32 v120, 0x3fb8aa3b, v120
	s_waitcnt lgkmcnt(1)
	v_fmac_f32_e32 v121, 0x3e000000, v123
	v_cndmask_b32_e64 v224, v164, v120, s[40:41]
	v_mul_f32_e32 v121, 0x3fb8aa3b, v121
	s_waitcnt lgkmcnt(0)
	v_fmac_f32_e32 v228, 0x3e000000, v130
	v_mul_f32_e32 v130, 0x3fb8aa3b, v228
	v_cndmask_b32_e64 v228, 0, v213, s[52:53]
	v_lshlrev_b32_e32 v228, 2, v228
	ds_read_b32 v228, v228 offset:18432
	v_cndmask_b32_e64 v130, v164, v130, s[54:55]
	v_cndmask_b32_e64 v220, v164, v121, s[36:37]
	s_waitcnt lgkmcnt(0)
	v_fmac_f32_e32 v228, 0x3e000000, v131
	v_mul_f32_e32 v131, 0x3fb8aa3b, v228
	v_cndmask_b32_e64 v228, v164, v131, s[52:53]
	v_max3_f32 v131, v229, v130, v228
	v_max3_f32 v120, v131, v225, v224
	v_max3_f32 v120, v120, v222, v220
	ds_bpermute_b32 v121, v207, v120
	s_waitcnt lgkmcnt(0)
	v_max_f32_e32 v121, v121, v121
	v_max_f32_e32 v120, v120, v121
	ds_bpermute_b32 v121, v214, v120
	s_waitcnt lgkmcnt(0)
	v_max3_f32 v229, v186, v120, v121
	v_cmp_gt_f32_e32 vcc, v229, v186
	s_cbranch_vccz .LBB0_515
	v_sub_f32_e32 v120, v186, v229
	v_exp_f32_e32 v120, v120
	v_mov_b32_e32 v186, v229
	v_mul_f32_e32 v166, v166, v120
	v_pk_mul_f32 v[34:35], v[34:35], v[120:121] op_sel_hi:[1,0]
	v_pk_mul_f32 v[32:33], v[32:33], v[120:121] op_sel_hi:[1,0]
	v_pk_mul_f32 v[30:31], v[30:31], v[120:121] op_sel_hi:[1,0]
	v_pk_mul_f32 v[28:29], v[28:29], v[120:121] op_sel_hi:[1,0]
	v_pk_mul_f32 v[22:23], v[22:23], v[120:121] op_sel_hi:[1,0]
	v_pk_mul_f32 v[20:21], v[20:21], v[120:121] op_sel_hi:[1,0]
	v_pk_mul_f32 v[18:19], v[18:19], v[120:121] op_sel_hi:[1,0]
	v_pk_mul_f32 v[16:17], v[16:17], v[120:121] op_sel_hi:[1,0]

; template <int DH, int KT, int NQT, bool PF, class Ctx>
; __device__ __forceinline__ void attn_item(unsigned char* smem, const Ctx& c) {
;     ...
;     __syncthreads();
;     if constexpr (PF) {
;       static_assert(!PF || NCH == 2 || NCH == 4, "wait lists below are written for two or four chunks per matrix");
;       if constexpr (NCH == 2) asm volatile("s_waitcnt vmcnt(0)" : "+v"(rk[0]), "+v"(rk[NCH - 1]), "+v"(rv[0]), "+v"(rv[NCH - 1]) :: "memory");
;       else asm volatile("s_waitcnt vmcnt(0)" : "+v"(rk[0]), "+v"(rk[1]), "+v"(rk[NCH - 2]), "+v"(rk[NCH - 1]), "+v"(rv[0]), "+v"(rv[1]), "+v"(rv[NCH - 2]), "+v"(rv[NCH - 1]) :: "memory");
; #pragma unroll
;       for (int i = 0; i < NCH; ++i) {
;         const int ci = tid + 256 * i, row = ci / CH, ch = ci % CH;
;         *(u32x4*)(sK + row * LDK + ch * 8) = rk[i]; *(u32x4*)(sV + row * LDK + ch * 8) = rv[i];
;       }
;     } else {
; #pragma unroll
;       for (int i = 0; i < NCH; ++i) {
;         const int ci = tid + 256 * i, row = ci / CH, ch = ci % CH;
;         *(u32x4*)(sK + row * LDK + ch * 8) = ld_agent_u32x4(c.kptr(t, row) + ch * 8);
;       }
; #pragma unroll
;       for (int i = 0; i < NCH; ++i) {
;         const int ci = tid + 256 * i, row = ci / CH, ch = ci % CH;
;         *(u32x4*)(sV + row * LDK + ch * 8) = ld_agent_u32x4(c.vptr(t, row) + ch * 8);
;       }
;     }
;     __syncthreads();
;     if constexpr (PF) {
;       if (t + 1 < nt) {
; #pragma unroll
;         for (int i = 0; i < NCH; ++i) {
;           const int ci = tid + 256 * i, row = ci / CH, ch = ci % CH;
;           ld16_sc1(rk[i], c.kptr(t + 1, row) + ch * 8); ld16_sc1(rv[i], c.vptr(t + 1, row) + ch * 8);
;         }
;       }
;     }
;     if (c.active(t, wid)) {
;       constexpr int QG = NQT < 2 ? NQT : 2;
;       bf16x8 pfa[NQT][NKK];
; #pragma unroll
;       for (int g = 0; g < NQT; g += QG) {
;         f32x4 s[QG][NK4];
; #pragma unroll
;         for (int q = 0; q < QG; ++q)
; #pragma unroll
;           for (int k4 = 0; k4 < NK4; ++k4) s[q][k4] = (f32x4){0.f, 0.f, 0.f, 0.f};
; #pragma unroll
;         for (int k4 = 0; k4 < NK4; ++k4)
; #pragma unroll
;           for (int ks = 0; ks < NKS; ++ks) {
;             const bf16x8 kf = *(const bf16x8*)(sK + (16 * k4 + l15) * LDK + ks * 32 + quad * 8);
; #pragma unroll
.LBB0_617:
	s_barrier
	s_waitcnt vmcnt(0)
	ds_write_b128 v157, v[96:99]
	ds_write_b128 v157, v[100:103] offset:16896
	ds_write_b128 v158, v[104:107]
	ds_write_b128 v158, v[108:111] offset:16896
	ds_write_b128 v159, v[112:115]
	ds_write_b128 v159, v[116:119] offset:16896
	ds_write_b128 v160, v[120:123]
	ds_write_b128 v160, v[124:127] offset:16896
	v_lshl_add_u64 v[96:97], v[146:147], 0, s[12:13]
	v_lshl_add_u64 v[100:101], v[132:133], 1, v[96:97]
	v_lshl_add_u64 v[96:97], v[100:101], 0, s[8:9]
	v_lshl_add_u64 v[104:105], v[144:145], 0, s[12:13]
	s_waitcnt lgkmcnt(0)
	s_barrier
	global_load_dwordx4 v[96:99], v[96:97], off sc1
	v_lshl_add_u64 v[100:101], v[100:101], 0, s[10:11]
	v_lshl_add_u64 v[108:109], v[134:135], 1, v[104:105]
	global_load_dwordx4 v[100:103], v[100:101], off sc1
	v_lshl_add_u64 v[104:105], v[108:109], 0, s[8:9]
	v_lshl_add_u64 v[112:113], v[142:143], 0, s[12:13]
	global_load_dwordx4 v[104:107], v[104:105], off sc1
	v_lshl_add_u64 v[108:109], v[108:109], 0, s[10:11]
	v_lshl_add_u64 v[116:117], v[136:137], 1, v[112:113]
	global_load_dwordx4 v[108:111], v[108:109], off sc1
	v_lshl_add_u64 v[112:113], v[116:117], 0, s[8:9]
	v_lshl_add_u64 v[120:121], v[140:141], 0, s[12:13]
	global_load_dwordx4 v[112:115], v[112:113], off sc1
	v_lshl_add_u64 v[116:117], v[116:117], 0, s[10:11]
	v_lshl_add_u64 v[124:125], v[138:139], 1, v[120:121]
	global_load_dwordx4 v[116:119], v[116:117], off sc1
	v_lshl_add_u64 v[120:121], v[124:125], 0, s[8:9]
	global_load_dwordx4 v[120:123], v[120:121], off sc1
	v_lshl_add_u64 v[124:125], v[124:125], 0, s[10:11]
	global_load_dwordx4 v[124:127], v[124:125], off sc1
	ds_read_b128 v[162:165], v156
	ds_read_b128 v[166:169], v156 offset:64
	s_waitcnt lgkmcnt(1)
	v_mfma_f32_16x16x32_bf16 v[162:165], v[162:165], v[72:75], 0
	ds_read_b128 v[170:173], v156 offset:128
	ds_read_b128 v[174:177], v156 offset:8576
	v_cmp_lt_i32_e32 vcc, v149, v150
	s_waitcnt lgkmcnt(2)
	v_mfma_f32_16x16x32_bf16 v[162:165], v[166:169], v[76:79], v[162:165]
	ds_read_b128 v[166:169], v156 offset:192
	v_cndmask_b32_e32 v154, v148, v149, vcc
	v_lshlrev_b32_e32 v154, 2, v154
	s_waitcnt lgkmcnt(2)
	v_mfma_f32_16x16x32_bf16 v[162:165], v[170:173], v[64:67], v[162:165]
	ds_read_b128 v[170:173], v156 offset:256
	v_cmp_lt_i32_e32 vcc, v151, v150
	s_waitcnt lgkmcnt(1)
	v_mfma_f32_16x16x32_bf16 v[162:165], v[166:169], v[68:71], v[162:165]
	ds_read_b128 v[166:169], v156 offset:320
	s_waitcnt lgkmcnt(1)
	v_mfma_f32_16x16x32_bf16 v[162:165], v[170:173], v[80:83], v[162:165]
	ds_read_b128 v[170:173], v156 offset:384
	s_waitcnt lgkmcnt(1)
	v_mfma_f32_16x16x32_bf16 v[162:165], v[166:169], v[84:87], v[162:165]
	ds_read_b128 v[166:169], v156 offset:448
	s_waitcnt lgkmcnt(1)
	v_mfma_f32_16x16x32_bf16 v[162:165], v[170:173], v[88:91], v[162:165]
	ds_read_b128 v[170:173], v156 offset:8448
	s_waitcnt lgkmcnt(1)
	v_mfma_f32_16x16x32_bf16 v[162:165], v[166:169], v[92:95], v[162:165]
	ds_read_b128 v[166:169], v156 offset:8512
	s_waitcnt lgkmcnt(1)
	v_mfma_f32_16x16x32_bf16 v[170:173], v[170:173], v[72:75], 0
	s_waitcnt lgkmcnt(0)
	v_mfma_f32_16x16x32_bf16 v[166:169], v[166:169], v[76:79], v[170:173]
	s_nop 5
	ds_read_b128 v[170:173], v156 offset:8640
	v_mfma_f32_16x16x32_bf16 v[166:169], v[174:177], v[64:67], v[166:169]
	ds_read_b128 v[174:177], v156 offset:8704
	s_waitcnt lgkmcnt(1)
	v_mfma_f32_16x16x32_bf16 v[166:169], v[170:173], v[68:71], v[166:169]
	ds_read_b128 v[170:173], v156 offset:8768
	s_waitcnt lgkmcnt(1)
	v_mfma_f32_16x16x32_bf16 v[166:169], v[174:177], v[80:83], v[166:169]
	ds_read_b128 v[174:177], v156 offset:8832
	s_waitcnt lgkmcnt(1)
	v_mfma_f32_16x16x32_bf16 v[166:169], v[170:173], v[84:87], v[166:169]
	ds_read_b128 v[170:173], v156 offset:8896
	s_waitcnt lgkmcnt(1)
	v_mfma_f32_16x16x32_bf16 v[166:169], v[174:177], v[88:91], v[166:169]
	s_waitcnt lgkmcnt(0)
	v_mfma_f32_16x16x32_bf16 v[170:173], v[170:173], v[92:95], v[166:169]
	s_nop 5
	v_mul_f32_e32 v169, 0x3db8aa3b, v162
	v_mul_f32_e32 v168, 0x3db8aa3b, v163
	v_max3_f32 v155, v169, s21, v168
	v_mul_f32_e32 v167, 0x3db8aa3b, v164
	v_mul_f32_e32 v166, 0x3db8aa3b, v165
	v_max3_f32 v155, v155, v167, v166
	v_mul_f32_e32 v165, 0x3db8aa3b, v170
	v_mul_f32_e32 v163, 0x3db8aa3b, v171
	v_max3_f32 v155, v155, v165, v163
	v_mul_f32_e32 v164, 0x3db8aa3b, v172
	v_mul_f32_e32 v162, 0x3db8aa3b, v173
	v_max3_f32 v170, v155, v164, v162
	ds_bpermute_b32 v171, v154, v170
	v_cndmask_b32_e32 v155, v148, v151, vcc
	v_lshlrev_b32_e32 v155, 2, v155
	s_waitcnt lgkmcnt(0)
	v_max_f32_e32 v171, v171, v171
	v_max_f32_e32 v170, v170, v171
	ds_bpermute_b32 v171, v155, v170
	s_waitcnt lgkmcnt(0)
	v_max3_f32 v170, v161, v170, v171
	v_cmp_gt_f32_e32 vcc, v170, v161
	s_cbranch_vccz .LBB0_616
	v_sub_f32_e32 v161, v161, v170
	v_exp_f32_e32 v172, v161
	v_mov_b32_e32 v161, v170
	v_pk_mul_f32 v[62:63], v[62:63], v[172:173] op_sel_hi:[1,0]
	v_pk_mul_f32 v[60:61], v[60:61], v[172:173] op_sel_hi:[1,0]
	v_pk_mul_f32 v[58:59], v[58:59], v[172:173] op_sel_hi:[1,0]
	v_pk_mul_f32 v[56:57], v[56:57], v[172:173] op_sel_hi:[1,0]
	v_pk_mul_f32 v[54:55], v[54:55], v[172:173] op_sel_hi:[1,0]
	v_pk_mul_f32 v[52:53], v[52:53], v[172:173] op_sel_hi:[1,0]
	v_pk_mul_f32 v[50:51], v[50:51], v[172:173] op_sel_hi:[1,0]
	v_pk_mul_f32 v[48:49], v[48:49], v[172:173] op_sel_hi:[1,0]
	v_pk_mul_f32 v[46:47], v[46:47], v[172:173] op_sel_hi:[1,0]
	v_pk_mul_f32 v[44:45], v[44:45], v[172:173] op_sel_hi:[1,0]
	v_pk_mul_f32 v[42:43], v[42:43], v[172:173] op_sel_hi:[1,0]
	v_pk_mul_f32 v[40:41], v[40:41], v[172:173] op_sel_hi:[1,0]
	v_pk_mul_f32 v[38:39], v[38:39], v[172:173] op_sel_hi:[1,0]
	v_pk_mul_f32 v[36:37], v[36:37], v[172:173] op_sel_hi:[1,0]
	v_pk_mul_f32 v[34:35], v[34:35], v[172:173] op_sel_hi:[1,0]
	v_pk_mul_f32 v[32:33], v[32:33], v[172:173] op_sel_hi:[1,0]
	v_pk_mul_f32 v[30:31], v[30:31], v[172:173] op_sel_hi:[1,0]
	v_pk_mul_f32 v[28:29], v[28:29], v[172:173] op_sel_hi:[1,0]
	v_pk_mul_f32 v[26:27], v[26:27], v[172:173] op_sel_hi:[1,0]
	v_pk_mul_f32 v[24:25], v[24:25], v[172:173] op_sel_hi:[1,0]
	v_pk_mul_f32 v[22:23], v[22:23], v[172:173] op_sel_hi:[1,0]
	v_pk_mul_f32 v[20:21], v[20:21], v[172:173] op_sel_hi:[1,0]
	v_pk_mul_f32 v[18:19], v[18:19], v[172:173] op_sel_hi:[1,0]
	v_pk_mul_f32 v[16:17], v[16:17], v[172:173] op_sel_hi:[1,0]
	v_pk_mul_f32 v[14:15], v[14:15], v[172:173] op_sel_hi:[1,0]
	v_pk_mul_f32 v[12:13], v[12:13], v[172:173] op_sel_hi:[1,0]
	v_pk_mul_f32 v[10:11], v[10:11], v[172:173] op_sel_hi:[1,0]
	v_pk_mul_f32 v[8:9], v[8:9], v[172:173] op_sel_hi:[1,0]
	v_pk_mul_f32 v[6:7], v[6:7], v[172:173] op_sel_hi:[1,0]
	v_pk_mul_f32 v[4:5], v[4:5], v[172:173] op_sel_hi:[1,0]
	v_pk_mul_f32 v[2:3], v[2:3], v[172:173] op_sel_hi:[1,0]
	v_pk_mul_f32 v[0:1], v[0:1], v[172:173] op_sel_hi:[1,0]
	v_mul_f32_e32 v128, v128, v172
	s_branch .LBB0_616
